# tail: first leftover-copy draw issued before the last thin stage (plus K-loop saddr addressing, S4 rstd table, deferred draw waits, P1 header wait removal)
# baseline (speedup 1.0000x reference)
.LBB0_1114:
	s_waitcnt vmcnt(0)
	s_barrier
	s_and_saveexec_b64 s[6:7], s[80:81]
	s_cbranch_execz .LBB0_1129
	v_readlane_b32 s98, v246, 2
	v_readlane_b32 s99, v246, 3
	s_add_u32 s98, s98, 0x3e40
	s_addc_u32 s99, s99, 0
	v_mov_b32_e32 v248, 0
	v_mov_b32_e32 v247, 1
	s_mov_b32 s100, 1
	global_atomic_add v247, v248, v247, s[98:99] sc0
	s_add_i32 s0, 0, 0x20164
	v_mov_b32_e32 v2, s0
	v_readlane_b32 s0, v246, 2
	v_mov_b32_e32 v3, 0x3000
	v_readlane_b32 s1, v246, 3
	ds_read_b32 v2, v2
	s_add_u32 s10, s0, 0x32c0
	s_addc_u32 s11, s1, 0
	s_nop 1
	global_load_dword v3, v3, s[0:1] offset:704 sc1
	buffer_inv sc1
	s_waitcnt vmcnt(0) lgkmcnt(0)
	v_cmp_ge_u32_e32 vcc, v3, v2
	s_cbranch_vccnz .LBB0_1129
	v_readlane_b32 s0, v246, 2
	v_readlane_b32 s1, v246, 3
	s_add_u32 s8, s0, 0x4200
	s_addc_u32 s9, s1, 0
	s_mov_b32 s0, 1
	v_mov_b32_e32 v3, 0
	s_branch .LBB0_1118

.LBB0_1132:
	s_and_saveexec_b64 s[12:13], s[80:81]
	s_cbranch_execz .LBB0_1136
	s_mov_b64 s[14:15], exec
	v_mbcnt_lo_u32_b32 v2, s14, 0
	v_mbcnt_hi_u32_b32 v2, s15, v2
	v_cmp_eq_u32_e32 vcc, 0, v2
	s_and_saveexec_b64 s[4:5], vcc
	s_cbranch_execz .LBB0_1135
	s_cmp_eq_u32 s100, 1
	s_cbranch_scc0 .Ltail_draw
	s_mov_b32 s100, 0
	v_mov_b32_e32 v6, v247
	s_branch .LBB0_1135
.Ltail_draw:
	s_bcnt1_i32_b64 s6, s[14:15]
	v_mov_b32_e32 v6, s6
	global_atomic_add v6, v3, v6, s[0:1] sc0
